# accumulator clearing between tiles with 64 v_pk_mov_b32 instead of 128 v_mov_b32
# speedup vs baseline: 1.0026x; 1.0026x over previous
.LBB0_234:
	v_mov_b32_e32 v129, 0
	v_mov_b32_e32 v128, v129
	s_andn2_b64 vcc, exec, s[24:25]
	v_pk_mov_b32 v[126:127], v[128:129], v[128:129]
	v_pk_mov_b32 v[124:125], v[128:129], v[128:129]
	v_pk_mov_b32 v[122:123], v[128:129], v[128:129]
	v_pk_mov_b32 v[112:113], v[128:129], v[128:129]
	v_pk_mov_b32 v[110:111], v[128:129], v[128:129]
	v_pk_mov_b32 v[108:109], v[128:129], v[128:129]
	v_pk_mov_b32 v[106:107], v[128:129], v[128:129]
	v_pk_mov_b32 v[96:97], v[128:129], v[128:129]
	v_pk_mov_b32 v[94:95], v[128:129], v[128:129]
	v_pk_mov_b32 v[92:93], v[128:129], v[128:129]
	v_pk_mov_b32 v[90:91], v[128:129], v[128:129]
	v_pk_mov_b32 v[80:81], v[128:129], v[128:129]
	v_pk_mov_b32 v[78:79], v[128:129], v[128:129]
	v_pk_mov_b32 v[76:77], v[128:129], v[128:129]
	v_pk_mov_b32 v[74:75], v[128:129], v[128:129]
	v_pk_mov_b32 v[120:121], v[128:129], v[128:129]
	v_pk_mov_b32 v[118:119], v[128:129], v[128:129]
	v_pk_mov_b32 v[116:117], v[128:129], v[128:129]
	v_pk_mov_b32 v[114:115], v[128:129], v[128:129]
	v_pk_mov_b32 v[104:105], v[128:129], v[128:129]
	v_pk_mov_b32 v[102:103], v[128:129], v[128:129]
	v_pk_mov_b32 v[100:101], v[128:129], v[128:129]
	v_pk_mov_b32 v[98:99], v[128:129], v[128:129]
	v_pk_mov_b32 v[88:89], v[128:129], v[128:129]
	v_pk_mov_b32 v[86:87], v[128:129], v[128:129]
	v_pk_mov_b32 v[84:85], v[128:129], v[128:129]
	v_pk_mov_b32 v[82:83], v[128:129], v[128:129]
	v_pk_mov_b32 v[72:73], v[128:129], v[128:129]
	v_pk_mov_b32 v[70:71], v[128:129], v[128:129]
	v_pk_mov_b32 v[68:69], v[128:129], v[128:129]
	v_pk_mov_b32 v[66:67], v[128:129], v[128:129]
	v_pk_mov_b32 v[64:65], v[128:129], v[128:129]
	v_pk_mov_b32 v[62:63], v[128:129], v[128:129]
	v_pk_mov_b32 v[60:61], v[128:129], v[128:129]
	v_pk_mov_b32 v[58:59], v[128:129], v[128:129]
	v_pk_mov_b32 v[48:49], v[128:129], v[128:129]
	v_pk_mov_b32 v[46:47], v[128:129], v[128:129]
	v_pk_mov_b32 v[44:45], v[128:129], v[128:129]
	v_pk_mov_b32 v[42:43], v[128:129], v[128:129]
	v_pk_mov_b32 v[32:33], v[128:129], v[128:129]
	v_pk_mov_b32 v[30:31], v[128:129], v[128:129]
	v_pk_mov_b32 v[28:29], v[128:129], v[128:129]
	v_pk_mov_b32 v[26:27], v[128:129], v[128:129]
	v_pk_mov_b32 v[16:17], v[128:129], v[128:129]
	v_pk_mov_b32 v[14:15], v[128:129], v[128:129]
	v_pk_mov_b32 v[12:13], v[128:129], v[128:129]
	v_pk_mov_b32 v[10:11], v[128:129], v[128:129]
	v_pk_mov_b32 v[56:57], v[128:129], v[128:129]
	v_pk_mov_b32 v[54:55], v[128:129], v[128:129]
	v_pk_mov_b32 v[52:53], v[128:129], v[128:129]
	v_pk_mov_b32 v[50:51], v[128:129], v[128:129]
	v_pk_mov_b32 v[40:41], v[128:129], v[128:129]
	v_pk_mov_b32 v[38:39], v[128:129], v[128:129]
	v_pk_mov_b32 v[36:37], v[128:129], v[128:129]
	v_pk_mov_b32 v[34:35], v[128:129], v[128:129]
	v_pk_mov_b32 v[24:25], v[128:129], v[128:129]
	v_pk_mov_b32 v[22:23], v[128:129], v[128:129]
	v_pk_mov_b32 v[20:21], v[128:129], v[128:129]
	v_pk_mov_b32 v[18:19], v[128:129], v[128:129]
	v_pk_mov_b32 v[8:9], v[128:129], v[128:129]
	v_pk_mov_b32 v[6:7], v[128:129], v[128:129]
	v_pk_mov_b32 v[4:5], v[128:129], v[128:129]
	v_pk_mov_b32 v[2:3], v[128:129], v[128:129]
	s_cbranch_vccnz .LBB0_237
	s_add_u32 s6, s10, 0x80
	s_addc_u32 s7, s11, 0
	s_add_u32 s10, s8, 0x100
	v_mov_b32_e32 v2, 0
	v_mov_b32_e32 v3, v2
	s_addc_u32 s11, s9, 0
	s_mov_b32 s2, 0
	v_pk_mov_b32 v[4:5], v[2:3], v[2:3]
	v_pk_mov_b32 v[6:7], v[2:3], v[2:3]
	v_pk_mov_b32 v[8:9], v[2:3], v[2:3]
	v_pk_mov_b32 v[18:19], v[2:3], v[2:3]
	v_pk_mov_b32 v[20:21], v[2:3], v[2:3]
	v_pk_mov_b32 v[22:23], v[2:3], v[2:3]
	v_pk_mov_b32 v[24:25], v[2:3], v[2:3]
	v_pk_mov_b32 v[34:35], v[2:3], v[2:3]
	v_pk_mov_b32 v[36:37], v[2:3], v[2:3]
	v_pk_mov_b32 v[38:39], v[2:3], v[2:3]
	v_pk_mov_b32 v[40:41], v[2:3], v[2:3]
	v_pk_mov_b32 v[50:51], v[2:3], v[2:3]
	v_pk_mov_b32 v[52:53], v[2:3], v[2:3]
	v_pk_mov_b32 v[54:55], v[2:3], v[2:3]
	v_pk_mov_b32 v[56:57], v[2:3], v[2:3]
	v_pk_mov_b32 v[10:11], v[2:3], v[2:3]
	v_pk_mov_b32 v[12:13], v[2:3], v[2:3]
	v_pk_mov_b32 v[14:15], v[2:3], v[2:3]
	v_pk_mov_b32 v[16:17], v[2:3], v[2:3]
	v_pk_mov_b32 v[26:27], v[2:3], v[2:3]
	v_pk_mov_b32 v[28:29], v[2:3], v[2:3]
	v_pk_mov_b32 v[30:31], v[2:3], v[2:3]
	v_pk_mov_b32 v[32:33], v[2:3], v[2:3]
	v_pk_mov_b32 v[42:43], v[2:3], v[2:3]
	v_pk_mov_b32 v[44:45], v[2:3], v[2:3]
	v_pk_mov_b32 v[46:47], v[2:3], v[2:3]
	v_pk_mov_b32 v[48:49], v[2:3], v[2:3]
	v_pk_mov_b32 v[58:59], v[2:3], v[2:3]
	v_pk_mov_b32 v[60:61], v[2:3], v[2:3]
	v_pk_mov_b32 v[62:63], v[2:3], v[2:3]
	v_pk_mov_b32 v[64:65], v[2:3], v[2:3]
	v_pk_mov_b32 v[66:67], v[2:3], v[2:3]
	v_pk_mov_b32 v[68:69], v[2:3], v[2:3]
	v_pk_mov_b32 v[70:71], v[2:3], v[2:3]
	v_pk_mov_b32 v[72:73], v[2:3], v[2:3]
	v_pk_mov_b32 v[82:83], v[2:3], v[2:3]
	v_pk_mov_b32 v[84:85], v[2:3], v[2:3]
	v_pk_mov_b32 v[86:87], v[2:3], v[2:3]
	v_pk_mov_b32 v[88:89], v[2:3], v[2:3]
	v_pk_mov_b32 v[98:99], v[2:3], v[2:3]
	v_pk_mov_b32 v[100:101], v[2:3], v[2:3]
	v_pk_mov_b32 v[102:103], v[2:3], v[2:3]
	v_pk_mov_b32 v[104:105], v[2:3], v[2:3]
	v_pk_mov_b32 v[114:115], v[2:3], v[2:3]
	v_pk_mov_b32 v[116:117], v[2:3], v[2:3]
	v_pk_mov_b32 v[118:119], v[2:3], v[2:3]
	v_pk_mov_b32 v[120:121], v[2:3], v[2:3]
	v_pk_mov_b32 v[74:75], v[2:3], v[2:3]
	v_pk_mov_b32 v[76:77], v[2:3], v[2:3]
	v_pk_mov_b32 v[78:79], v[2:3], v[2:3]
	v_pk_mov_b32 v[80:81], v[2:3], v[2:3]
	v_pk_mov_b32 v[90:91], v[2:3], v[2:3]
	v_pk_mov_b32 v[92:93], v[2:3], v[2:3]
	v_pk_mov_b32 v[94:95], v[2:3], v[2:3]
	v_pk_mov_b32 v[96:97], v[2:3], v[2:3]
	v_pk_mov_b32 v[106:107], v[2:3], v[2:3]
	v_pk_mov_b32 v[108:109], v[2:3], v[2:3]
	v_pk_mov_b32 v[110:111], v[2:3], v[2:3]
	v_pk_mov_b32 v[112:113], v[2:3], v[2:3]
	v_pk_mov_b32 v[122:123], v[2:3], v[2:3]
	v_pk_mov_b32 v[124:125], v[2:3], v[2:3]
	v_pk_mov_b32 v[126:127], v[2:3], v[2:3]
	v_pk_mov_b32 v[128:129], v[2:3], v[2:3]
	v_add_u32_e32 v243, s18, v130
	v_add_u32_e32 v242, s18, v132

.LBB0_995:
	v_mov_b32_e32 v129, 0
	v_mov_b32_e32 v128, v129
	s_and_b64 vcc, exec, s[6:7]
	v_pk_mov_b32 v[126:127], v[128:129], v[128:129]
	v_pk_mov_b32 v[124:125], v[128:129], v[128:129]
	v_pk_mov_b32 v[122:123], v[128:129], v[128:129]
	v_pk_mov_b32 v[112:113], v[128:129], v[128:129]
	v_pk_mov_b32 v[110:111], v[128:129], v[128:129]
	v_pk_mov_b32 v[108:109], v[128:129], v[128:129]
	v_pk_mov_b32 v[106:107], v[128:129], v[128:129]
	v_pk_mov_b32 v[96:97], v[128:129], v[128:129]
	v_pk_mov_b32 v[94:95], v[128:129], v[128:129]
	v_pk_mov_b32 v[92:93], v[128:129], v[128:129]
	v_pk_mov_b32 v[90:91], v[128:129], v[128:129]
	v_pk_mov_b32 v[80:81], v[128:129], v[128:129]
	v_pk_mov_b32 v[78:79], v[128:129], v[128:129]
	v_pk_mov_b32 v[76:77], v[128:129], v[128:129]
	v_pk_mov_b32 v[74:75], v[128:129], v[128:129]
	v_pk_mov_b32 v[120:121], v[128:129], v[128:129]
	v_pk_mov_b32 v[118:119], v[128:129], v[128:129]
	v_pk_mov_b32 v[116:117], v[128:129], v[128:129]
	v_pk_mov_b32 v[114:115], v[128:129], v[128:129]
	v_pk_mov_b32 v[104:105], v[128:129], v[128:129]
	v_pk_mov_b32 v[102:103], v[128:129], v[128:129]
	v_pk_mov_b32 v[100:101], v[128:129], v[128:129]
	v_pk_mov_b32 v[98:99], v[128:129], v[128:129]
	v_pk_mov_b32 v[88:89], v[128:129], v[128:129]
	v_pk_mov_b32 v[86:87], v[128:129], v[128:129]
	v_pk_mov_b32 v[84:85], v[128:129], v[128:129]
	v_pk_mov_b32 v[82:83], v[128:129], v[128:129]
	v_pk_mov_b32 v[72:73], v[128:129], v[128:129]
	v_pk_mov_b32 v[70:71], v[128:129], v[128:129]
	v_pk_mov_b32 v[68:69], v[128:129], v[128:129]
	v_pk_mov_b32 v[66:67], v[128:129], v[128:129]
	v_pk_mov_b32 v[64:65], v[128:129], v[128:129]
	v_pk_mov_b32 v[62:63], v[128:129], v[128:129]
	v_pk_mov_b32 v[60:61], v[128:129], v[128:129]
	v_pk_mov_b32 v[58:59], v[128:129], v[128:129]
	v_pk_mov_b32 v[48:49], v[128:129], v[128:129]
	v_pk_mov_b32 v[46:47], v[128:129], v[128:129]
	v_pk_mov_b32 v[44:45], v[128:129], v[128:129]
	v_pk_mov_b32 v[42:43], v[128:129], v[128:129]
	v_pk_mov_b32 v[32:33], v[128:129], v[128:129]
	v_pk_mov_b32 v[30:31], v[128:129], v[128:129]
	v_pk_mov_b32 v[28:29], v[128:129], v[128:129]
	v_pk_mov_b32 v[26:27], v[128:129], v[128:129]
	v_pk_mov_b32 v[16:17], v[128:129], v[128:129]
	v_pk_mov_b32 v[14:15], v[128:129], v[128:129]
	v_pk_mov_b32 v[12:13], v[128:129], v[128:129]
	v_pk_mov_b32 v[10:11], v[128:129], v[128:129]
	v_pk_mov_b32 v[56:57], v[128:129], v[128:129]
	v_pk_mov_b32 v[54:55], v[128:129], v[128:129]
	v_pk_mov_b32 v[52:53], v[128:129], v[128:129]
	v_pk_mov_b32 v[50:51], v[128:129], v[128:129]
	v_pk_mov_b32 v[40:41], v[128:129], v[128:129]
	v_pk_mov_b32 v[38:39], v[128:129], v[128:129]
	v_pk_mov_b32 v[36:37], v[128:129], v[128:129]
	v_pk_mov_b32 v[34:35], v[128:129], v[128:129]
	v_pk_mov_b32 v[24:25], v[128:129], v[128:129]
	v_pk_mov_b32 v[22:23], v[128:129], v[128:129]
	v_pk_mov_b32 v[20:21], v[128:129], v[128:129]
	v_pk_mov_b32 v[18:19], v[128:129], v[128:129]
	v_pk_mov_b32 v[8:9], v[128:129], v[128:129]
	v_pk_mov_b32 v[6:7], v[128:129], v[128:129]
	s_waitcnt lgkmcnt(0)
	v_pk_mov_b32 v[4:5], v[128:129], v[128:129]
	v_pk_mov_b32 v[2:3], v[128:129], v[128:129]
	s_cbranch_vccnz .LBB0_998
	s_add_u32 s24, s24, 0x80
	s_addc_u32 s25, s25, 0
	s_add_u32 s36, s26, 0x100
	v_mov_b32_e32 v2, 0
	v_mov_b32_e32 v3, v2
	s_addc_u32 s37, s27, 0
	s_mov_b32 s2, 0
	v_pk_mov_b32 v[4:5], v[2:3], v[2:3]
	v_pk_mov_b32 v[6:7], v[2:3], v[2:3]
	v_pk_mov_b32 v[8:9], v[2:3], v[2:3]
	v_pk_mov_b32 v[18:19], v[2:3], v[2:3]
	v_pk_mov_b32 v[20:21], v[2:3], v[2:3]
	v_pk_mov_b32 v[22:23], v[2:3], v[2:3]
	v_pk_mov_b32 v[24:25], v[2:3], v[2:3]
	v_pk_mov_b32 v[34:35], v[2:3], v[2:3]
	v_pk_mov_b32 v[36:37], v[2:3], v[2:3]
	v_pk_mov_b32 v[38:39], v[2:3], v[2:3]
	v_pk_mov_b32 v[40:41], v[2:3], v[2:3]
	v_pk_mov_b32 v[50:51], v[2:3], v[2:3]
	v_pk_mov_b32 v[52:53], v[2:3], v[2:3]
	v_pk_mov_b32 v[54:55], v[2:3], v[2:3]
	v_pk_mov_b32 v[56:57], v[2:3], v[2:3]
	v_pk_mov_b32 v[10:11], v[2:3], v[2:3]
	v_pk_mov_b32 v[12:13], v[2:3], v[2:3]
	v_pk_mov_b32 v[14:15], v[2:3], v[2:3]
	v_pk_mov_b32 v[16:17], v[2:3], v[2:3]
	v_pk_mov_b32 v[26:27], v[2:3], v[2:3]
	v_pk_mov_b32 v[28:29], v[2:3], v[2:3]
	v_pk_mov_b32 v[30:31], v[2:3], v[2:3]
	v_pk_mov_b32 v[32:33], v[2:3], v[2:3]
	v_pk_mov_b32 v[42:43], v[2:3], v[2:3]
	v_pk_mov_b32 v[44:45], v[2:3], v[2:3]
	v_pk_mov_b32 v[46:47], v[2:3], v[2:3]
	v_pk_mov_b32 v[48:49], v[2:3], v[2:3]
	v_pk_mov_b32 v[58:59], v[2:3], v[2:3]
	v_pk_mov_b32 v[60:61], v[2:3], v[2:3]
	v_pk_mov_b32 v[62:63], v[2:3], v[2:3]
	v_pk_mov_b32 v[64:65], v[2:3], v[2:3]
	v_pk_mov_b32 v[66:67], v[2:3], v[2:3]
	v_pk_mov_b32 v[68:69], v[2:3], v[2:3]
	v_pk_mov_b32 v[70:71], v[2:3], v[2:3]
	v_pk_mov_b32 v[72:73], v[2:3], v[2:3]
	v_pk_mov_b32 v[82:83], v[2:3], v[2:3]
	v_pk_mov_b32 v[84:85], v[2:3], v[2:3]
	v_pk_mov_b32 v[86:87], v[2:3], v[2:3]
	v_pk_mov_b32 v[88:89], v[2:3], v[2:3]
	v_pk_mov_b32 v[98:99], v[2:3], v[2:3]
	v_pk_mov_b32 v[100:101], v[2:3], v[2:3]
	v_pk_mov_b32 v[102:103], v[2:3], v[2:3]
	v_pk_mov_b32 v[104:105], v[2:3], v[2:3]
	v_pk_mov_b32 v[114:115], v[2:3], v[2:3]
	v_pk_mov_b32 v[116:117], v[2:3], v[2:3]
	v_pk_mov_b32 v[118:119], v[2:3], v[2:3]
	v_pk_mov_b32 v[120:121], v[2:3], v[2:3]
	v_pk_mov_b32 v[74:75], v[2:3], v[2:3]
	v_pk_mov_b32 v[76:77], v[2:3], v[2:3]
	v_pk_mov_b32 v[78:79], v[2:3], v[2:3]
	v_pk_mov_b32 v[80:81], v[2:3], v[2:3]
	v_pk_mov_b32 v[90:91], v[2:3], v[2:3]
	v_pk_mov_b32 v[92:93], v[2:3], v[2:3]
	v_pk_mov_b32 v[94:95], v[2:3], v[2:3]
	v_pk_mov_b32 v[96:97], v[2:3], v[2:3]
	v_pk_mov_b32 v[106:107], v[2:3], v[2:3]
	v_pk_mov_b32 v[108:109], v[2:3], v[2:3]
	v_pk_mov_b32 v[110:111], v[2:3], v[2:3]
	v_pk_mov_b32 v[112:113], v[2:3], v[2:3]
	v_pk_mov_b32 v[122:123], v[2:3], v[2:3]
	v_pk_mov_b32 v[124:125], v[2:3], v[2:3]
	v_pk_mov_b32 v[126:127], v[2:3], v[2:3]
	v_pk_mov_b32 v[128:129], v[2:3], v[2:3]
	v_add_u32_e32 v243, s16, v130
	v_add_u32_e32 v242, s16, v132

.LBB0_1102:
	v_mov_b32_e32 v137, 0
	v_mov_b32_e32 v136, v137
	s_and_b64 vcc, exec, s[4:5]
	v_pk_mov_b32 v[134:135], v[136:137], v[136:137]
	v_pk_mov_b32 v[120:121], v[136:137], v[136:137]
	v_pk_mov_b32 v[118:119], v[136:137], v[136:137]
	v_pk_mov_b32 v[112:113], v[136:137], v[136:137]
	v_pk_mov_b32 v[110:111], v[136:137], v[136:137]
	v_pk_mov_b32 v[104:105], v[136:137], v[136:137]
	v_pk_mov_b32 v[102:103], v[136:137], v[136:137]
	v_pk_mov_b32 v[96:97], v[136:137], v[136:137]
	v_pk_mov_b32 v[94:95], v[136:137], v[136:137]
	v_pk_mov_b32 v[88:89], v[136:137], v[136:137]
	v_pk_mov_b32 v[86:87], v[136:137], v[136:137]
	v_pk_mov_b32 v[80:81], v[136:137], v[136:137]
	v_pk_mov_b32 v[78:79], v[136:137], v[136:137]
	v_pk_mov_b32 v[72:73], v[136:137], v[136:137]
	v_pk_mov_b32 v[70:71], v[136:137], v[136:137]
	v_pk_mov_b32 v[132:133], v[136:137], v[136:137]
	v_pk_mov_b32 v[130:131], v[136:137], v[136:137]
	v_pk_mov_b32 v[116:117], v[136:137], v[136:137]
	v_pk_mov_b32 v[114:115], v[136:137], v[136:137]
	v_pk_mov_b32 v[108:109], v[136:137], v[136:137]
	v_pk_mov_b32 v[106:107], v[136:137], v[136:137]
	v_pk_mov_b32 v[100:101], v[136:137], v[136:137]
	v_pk_mov_b32 v[98:99], v[136:137], v[136:137]
	v_pk_mov_b32 v[92:93], v[136:137], v[136:137]
	v_pk_mov_b32 v[90:91], v[136:137], v[136:137]
	v_pk_mov_b32 v[84:85], v[136:137], v[136:137]
	v_pk_mov_b32 v[82:83], v[136:137], v[136:137]
	v_pk_mov_b32 v[76:77], v[136:137], v[136:137]
	v_pk_mov_b32 v[74:75], v[136:137], v[136:137]
	v_pk_mov_b32 v[68:69], v[136:137], v[136:137]
	v_pk_mov_b32 v[66:67], v[136:137], v[136:137]
	v_pk_mov_b32 v[64:65], v[136:137], v[136:137]
	v_pk_mov_b32 v[62:63], v[136:137], v[136:137]
	v_pk_mov_b32 v[56:57], v[136:137], v[136:137]
	v_pk_mov_b32 v[54:55], v[136:137], v[136:137]
	v_pk_mov_b32 v[48:49], v[136:137], v[136:137]
	v_pk_mov_b32 v[46:47], v[136:137], v[136:137]
	v_pk_mov_b32 v[40:41], v[136:137], v[136:137]
	v_pk_mov_b32 v[38:39], v[136:137], v[136:137]
	v_pk_mov_b32 v[32:33], v[136:137], v[136:137]
	v_pk_mov_b32 v[30:31], v[136:137], v[136:137]
	v_pk_mov_b32 v[24:25], v[136:137], v[136:137]
	v_pk_mov_b32 v[22:23], v[136:137], v[136:137]
	v_pk_mov_b32 v[16:17], v[136:137], v[136:137]
	v_pk_mov_b32 v[14:15], v[136:137], v[136:137]
	v_pk_mov_b32 v[8:9], v[136:137], v[136:137]
	v_pk_mov_b32 v[6:7], v[136:137], v[136:137]
	v_pk_mov_b32 v[60:61], v[136:137], v[136:137]
	v_pk_mov_b32 v[58:59], v[136:137], v[136:137]
	v_pk_mov_b32 v[52:53], v[136:137], v[136:137]
	v_pk_mov_b32 v[50:51], v[136:137], v[136:137]
	v_pk_mov_b32 v[44:45], v[136:137], v[136:137]
	v_pk_mov_b32 v[42:43], v[136:137], v[136:137]
	v_pk_mov_b32 v[36:37], v[136:137], v[136:137]
	v_pk_mov_b32 v[34:35], v[136:137], v[136:137]
	v_pk_mov_b32 v[28:29], v[136:137], v[136:137]
	v_pk_mov_b32 v[26:27], v[136:137], v[136:137]
	v_pk_mov_b32 v[20:21], v[136:137], v[136:137]
	v_pk_mov_b32 v[18:19], v[136:137], v[136:137]
	v_pk_mov_b32 v[12:13], v[136:137], v[136:137]
	v_pk_mov_b32 v[10:11], v[136:137], v[136:137]
	v_pk_mov_b32 v[4:5], v[136:137], v[136:137]
	v_pk_mov_b32 v[2:3], v[136:137], v[136:137]
	s_cbranch_vccnz .LBB0_1095
	s_add_u32 s0, s28, 0x80
	s_addc_u32 s1, s29, 0
	s_add_u32 s28, s26, 0x100
	v_mov_b32_e32 v2, 0
	v_mov_b32_e32 v3, v2
	s_addc_u32 s29, s27, 0
	s_mov_b32 s2, 0
	v_pk_mov_b32 v[4:5], v[2:3], v[2:3]
	v_pk_mov_b32 v[10:11], v[2:3], v[2:3]
	v_pk_mov_b32 v[12:13], v[2:3], v[2:3]
	v_pk_mov_b32 v[18:19], v[2:3], v[2:3]
	v_pk_mov_b32 v[20:21], v[2:3], v[2:3]
	v_pk_mov_b32 v[26:27], v[2:3], v[2:3]
	v_pk_mov_b32 v[28:29], v[2:3], v[2:3]
	v_pk_mov_b32 v[34:35], v[2:3], v[2:3]
	v_pk_mov_b32 v[36:37], v[2:3], v[2:3]
	v_pk_mov_b32 v[42:43], v[2:3], v[2:3]
	v_pk_mov_b32 v[44:45], v[2:3], v[2:3]
	v_pk_mov_b32 v[50:51], v[2:3], v[2:3]
	v_pk_mov_b32 v[52:53], v[2:3], v[2:3]
	v_pk_mov_b32 v[58:59], v[2:3], v[2:3]
	v_pk_mov_b32 v[60:61], v[2:3], v[2:3]
	v_pk_mov_b32 v[6:7], v[2:3], v[2:3]
	v_pk_mov_b32 v[8:9], v[2:3], v[2:3]
	v_pk_mov_b32 v[14:15], v[2:3], v[2:3]
	v_pk_mov_b32 v[16:17], v[2:3], v[2:3]
	v_pk_mov_b32 v[22:23], v[2:3], v[2:3]
	v_pk_mov_b32 v[24:25], v[2:3], v[2:3]
	v_pk_mov_b32 v[30:31], v[2:3], v[2:3]
	v_pk_mov_b32 v[32:33], v[2:3], v[2:3]
	v_pk_mov_b32 v[38:39], v[2:3], v[2:3]
	v_pk_mov_b32 v[40:41], v[2:3], v[2:3]
	v_pk_mov_b32 v[46:47], v[2:3], v[2:3]
	v_pk_mov_b32 v[48:49], v[2:3], v[2:3]
	v_pk_mov_b32 v[54:55], v[2:3], v[2:3]
	v_pk_mov_b32 v[56:57], v[2:3], v[2:3]
	v_pk_mov_b32 v[62:63], v[2:3], v[2:3]
	v_pk_mov_b32 v[64:65], v[2:3], v[2:3]
	v_pk_mov_b32 v[66:67], v[2:3], v[2:3]
	v_pk_mov_b32 v[68:69], v[2:3], v[2:3]
	v_pk_mov_b32 v[74:75], v[2:3], v[2:3]
	v_pk_mov_b32 v[76:77], v[2:3], v[2:3]
	v_pk_mov_b32 v[82:83], v[2:3], v[2:3]
	v_pk_mov_b32 v[84:85], v[2:3], v[2:3]
	v_pk_mov_b32 v[90:91], v[2:3], v[2:3]
	v_pk_mov_b32 v[92:93], v[2:3], v[2:3]
	v_pk_mov_b32 v[98:99], v[2:3], v[2:3]
	v_pk_mov_b32 v[100:101], v[2:3], v[2:3]
	v_pk_mov_b32 v[106:107], v[2:3], v[2:3]
	v_pk_mov_b32 v[108:109], v[2:3], v[2:3]
	v_pk_mov_b32 v[114:115], v[2:3], v[2:3]
	v_pk_mov_b32 v[116:117], v[2:3], v[2:3]
	v_pk_mov_b32 v[130:131], v[2:3], v[2:3]
	v_pk_mov_b32 v[132:133], v[2:3], v[2:3]
	v_pk_mov_b32 v[70:71], v[2:3], v[2:3]
	v_pk_mov_b32 v[72:73], v[2:3], v[2:3]
	v_pk_mov_b32 v[78:79], v[2:3], v[2:3]
	v_pk_mov_b32 v[80:81], v[2:3], v[2:3]
	v_pk_mov_b32 v[86:87], v[2:3], v[2:3]
	v_pk_mov_b32 v[88:89], v[2:3], v[2:3]
	v_pk_mov_b32 v[94:95], v[2:3], v[2:3]
	v_pk_mov_b32 v[96:97], v[2:3], v[2:3]
	v_pk_mov_b32 v[102:103], v[2:3], v[2:3]
	v_pk_mov_b32 v[104:105], v[2:3], v[2:3]
	v_pk_mov_b32 v[110:111], v[2:3], v[2:3]
	v_pk_mov_b32 v[112:113], v[2:3], v[2:3]
	v_pk_mov_b32 v[118:119], v[2:3], v[2:3]
	v_pk_mov_b32 v[120:121], v[2:3], v[2:3]
	v_pk_mov_b32 v[134:135], v[2:3], v[2:3]
	v_pk_mov_b32 v[136:137], v[2:3], v[2:3]
	v_add_u32_e32 v241, s22, v164
	v_add_u32_e32 v240, s22, v166

.LBB0_1147:
	v_mov_b32_e32 v129, 0
	v_mov_b32_e32 v128, v129
	s_and_b64 vcc, exec, s[6:7]
	v_pk_mov_b32 v[126:127], v[128:129], v[128:129]
	v_pk_mov_b32 v[124:125], v[128:129], v[128:129]
	v_pk_mov_b32 v[122:123], v[128:129], v[128:129]
	v_pk_mov_b32 v[112:113], v[128:129], v[128:129]
	v_pk_mov_b32 v[110:111], v[128:129], v[128:129]
	v_pk_mov_b32 v[108:109], v[128:129], v[128:129]
	v_pk_mov_b32 v[106:107], v[128:129], v[128:129]
	v_pk_mov_b32 v[96:97], v[128:129], v[128:129]
	v_pk_mov_b32 v[94:95], v[128:129], v[128:129]
	v_pk_mov_b32 v[92:93], v[128:129], v[128:129]
	v_pk_mov_b32 v[90:91], v[128:129], v[128:129]
	v_pk_mov_b32 v[80:81], v[128:129], v[128:129]
	v_pk_mov_b32 v[78:79], v[128:129], v[128:129]
	v_pk_mov_b32 v[76:77], v[128:129], v[128:129]
	v_pk_mov_b32 v[74:75], v[128:129], v[128:129]
	v_pk_mov_b32 v[120:121], v[128:129], v[128:129]
	v_pk_mov_b32 v[118:119], v[128:129], v[128:129]
	v_pk_mov_b32 v[116:117], v[128:129], v[128:129]
	v_pk_mov_b32 v[114:115], v[128:129], v[128:129]
	v_pk_mov_b32 v[104:105], v[128:129], v[128:129]
	v_pk_mov_b32 v[102:103], v[128:129], v[128:129]
	v_pk_mov_b32 v[100:101], v[128:129], v[128:129]
	v_pk_mov_b32 v[98:99], v[128:129], v[128:129]
	v_pk_mov_b32 v[88:89], v[128:129], v[128:129]
	v_pk_mov_b32 v[86:87], v[128:129], v[128:129]
	v_pk_mov_b32 v[84:85], v[128:129], v[128:129]
	v_pk_mov_b32 v[82:83], v[128:129], v[128:129]
	v_pk_mov_b32 v[72:73], v[128:129], v[128:129]
	v_pk_mov_b32 v[70:71], v[128:129], v[128:129]
	v_pk_mov_b32 v[68:69], v[128:129], v[128:129]
	v_pk_mov_b32 v[66:67], v[128:129], v[128:129]
	v_pk_mov_b32 v[64:65], v[128:129], v[128:129]
	v_pk_mov_b32 v[62:63], v[128:129], v[128:129]
	v_pk_mov_b32 v[60:61], v[128:129], v[128:129]
	v_pk_mov_b32 v[58:59], v[128:129], v[128:129]
	v_pk_mov_b32 v[48:49], v[128:129], v[128:129]
	v_pk_mov_b32 v[46:47], v[128:129], v[128:129]
	v_pk_mov_b32 v[44:45], v[128:129], v[128:129]
	v_pk_mov_b32 v[42:43], v[128:129], v[128:129]
	v_pk_mov_b32 v[32:33], v[128:129], v[128:129]
	v_pk_mov_b32 v[30:31], v[128:129], v[128:129]
	v_pk_mov_b32 v[28:29], v[128:129], v[128:129]
	v_pk_mov_b32 v[26:27], v[128:129], v[128:129]
	v_pk_mov_b32 v[16:17], v[128:129], v[128:129]
	v_pk_mov_b32 v[14:15], v[128:129], v[128:129]
	v_pk_mov_b32 v[12:13], v[128:129], v[128:129]
	v_pk_mov_b32 v[10:11], v[128:129], v[128:129]
	v_pk_mov_b32 v[56:57], v[128:129], v[128:129]
	v_pk_mov_b32 v[54:55], v[128:129], v[128:129]
	v_pk_mov_b32 v[52:53], v[128:129], v[128:129]
	v_pk_mov_b32 v[50:51], v[128:129], v[128:129]
	v_pk_mov_b32 v[40:41], v[128:129], v[128:129]
	v_pk_mov_b32 v[38:39], v[128:129], v[128:129]
	v_pk_mov_b32 v[36:37], v[128:129], v[128:129]
	v_pk_mov_b32 v[34:35], v[128:129], v[128:129]
	v_pk_mov_b32 v[24:25], v[128:129], v[128:129]
	v_pk_mov_b32 v[22:23], v[128:129], v[128:129]
	v_pk_mov_b32 v[20:21], v[128:129], v[128:129]
	v_pk_mov_b32 v[18:19], v[128:129], v[128:129]
	v_pk_mov_b32 v[8:9], v[128:129], v[128:129]
	v_pk_mov_b32 v[6:7], v[128:129], v[128:129]
	s_waitcnt lgkmcnt(0)
	v_pk_mov_b32 v[4:5], v[128:129], v[128:129]
	v_pk_mov_b32 v[2:3], v[128:129], v[128:129]
	s_cbranch_vccnz .LBB0_1150
	s_add_u32 s54, s28, 0x80
	s_addc_u32 s55, s29, 0
	s_add_u32 s28, s26, 0x100
	v_mov_b32_e32 v2, 0
	v_mov_b32_e32 v3, v2
	s_addc_u32 s29, s27, 0
	s_mov_b32 s2, 0
	v_pk_mov_b32 v[4:5], v[2:3], v[2:3]
	v_pk_mov_b32 v[6:7], v[2:3], v[2:3]
	v_pk_mov_b32 v[8:9], v[2:3], v[2:3]
	v_pk_mov_b32 v[18:19], v[2:3], v[2:3]
	v_pk_mov_b32 v[20:21], v[2:3], v[2:3]
	v_pk_mov_b32 v[22:23], v[2:3], v[2:3]
	v_pk_mov_b32 v[24:25], v[2:3], v[2:3]
	v_pk_mov_b32 v[34:35], v[2:3], v[2:3]
	v_pk_mov_b32 v[36:37], v[2:3], v[2:3]
	v_pk_mov_b32 v[38:39], v[2:3], v[2:3]
	v_pk_mov_b32 v[40:41], v[2:3], v[2:3]
	v_pk_mov_b32 v[50:51], v[2:3], v[2:3]
	v_pk_mov_b32 v[52:53], v[2:3], v[2:3]
	v_pk_mov_b32 v[54:55], v[2:3], v[2:3]
	v_pk_mov_b32 v[56:57], v[2:3], v[2:3]
	v_pk_mov_b32 v[10:11], v[2:3], v[2:3]
	v_pk_mov_b32 v[12:13], v[2:3], v[2:3]
	v_pk_mov_b32 v[14:15], v[2:3], v[2:3]
	v_pk_mov_b32 v[16:17], v[2:3], v[2:3]
	v_pk_mov_b32 v[26:27], v[2:3], v[2:3]
	v_pk_mov_b32 v[28:29], v[2:3], v[2:3]
	v_pk_mov_b32 v[30:31], v[2:3], v[2:3]
	v_pk_mov_b32 v[32:33], v[2:3], v[2:3]
	v_pk_mov_b32 v[42:43], v[2:3], v[2:3]
	v_pk_mov_b32 v[44:45], v[2:3], v[2:3]
	v_pk_mov_b32 v[46:47], v[2:3], v[2:3]
	v_pk_mov_b32 v[48:49], v[2:3], v[2:3]
	v_pk_mov_b32 v[58:59], v[2:3], v[2:3]
	v_pk_mov_b32 v[60:61], v[2:3], v[2:3]
	v_pk_mov_b32 v[62:63], v[2:3], v[2:3]
	v_pk_mov_b32 v[64:65], v[2:3], v[2:3]
	v_pk_mov_b32 v[66:67], v[2:3], v[2:3]
	v_pk_mov_b32 v[68:69], v[2:3], v[2:3]
	v_pk_mov_b32 v[70:71], v[2:3], v[2:3]
	v_pk_mov_b32 v[72:73], v[2:3], v[2:3]
	v_pk_mov_b32 v[82:83], v[2:3], v[2:3]
	v_pk_mov_b32 v[84:85], v[2:3], v[2:3]
	v_pk_mov_b32 v[86:87], v[2:3], v[2:3]
	v_pk_mov_b32 v[88:89], v[2:3], v[2:3]
	v_pk_mov_b32 v[98:99], v[2:3], v[2:3]
	v_pk_mov_b32 v[100:101], v[2:3], v[2:3]
	v_pk_mov_b32 v[102:103], v[2:3], v[2:3]
	v_pk_mov_b32 v[104:105], v[2:3], v[2:3]
	v_pk_mov_b32 v[114:115], v[2:3], v[2:3]
	v_pk_mov_b32 v[116:117], v[2:3], v[2:3]
	v_pk_mov_b32 v[118:119], v[2:3], v[2:3]
	v_pk_mov_b32 v[120:121], v[2:3], v[2:3]
	v_pk_mov_b32 v[74:75], v[2:3], v[2:3]
	v_pk_mov_b32 v[76:77], v[2:3], v[2:3]
	v_pk_mov_b32 v[78:79], v[2:3], v[2:3]
	v_pk_mov_b32 v[80:81], v[2:3], v[2:3]
	v_pk_mov_b32 v[90:91], v[2:3], v[2:3]
	v_pk_mov_b32 v[92:93], v[2:3], v[2:3]
	v_pk_mov_b32 v[94:95], v[2:3], v[2:3]
	v_pk_mov_b32 v[96:97], v[2:3], v[2:3]
	v_pk_mov_b32 v[106:107], v[2:3], v[2:3]
	v_pk_mov_b32 v[108:109], v[2:3], v[2:3]
	v_pk_mov_b32 v[110:111], v[2:3], v[2:3]
	v_pk_mov_b32 v[112:113], v[2:3], v[2:3]
	v_pk_mov_b32 v[122:123], v[2:3], v[2:3]
	v_pk_mov_b32 v[124:125], v[2:3], v[2:3]
	v_pk_mov_b32 v[126:127], v[2:3], v[2:3]
	v_pk_mov_b32 v[128:129], v[2:3], v[2:3]
